# diff-attn v128 max-free loop: 3 LDS-DMA requests per step spread into the QK/PV segments (after MFMA 2,6,12), m0 save/restore dropped; on top of v1
# baseline (speedup 1.0000x reference)
.LBB0_798:
	s_mov_b32 s8, s36
	s_mov_b32 s6, s10
	s_mov_b32 s7, s35
	v_add_f32_e32 v98, v82, v83
	v_add_f32_e32 v98, v84, v98
	v_add_f32_e32 v98, v85, v98
	v_add_f32_e32 v98, v86, v98
	v_add_f32_e32 v98, v87, v98
	v_cvt_pk_bf16_f32 v158, v82, v83
	v_cvt_pk_bf16_f32 v159, v84, v85
	v_lshl_add_u32 v201, s9, 1, v214
	s_waitcnt lgkmcnt(7)
	v_mfma_f32_32x32x16_bf16 v[114:129], v[186:189], v[154:157], 0
	s_nop 0
	v_add_f32_e32 v82, v88, v98
	v_add_f32_e32 v82, v89, v82
	v_add_f32_e32 v82, v90, v82
	v_add_f32_e32 v82, v91, v82
	v_cvt_pk_bf16_f32 v160, v86, v87
	v_cvt_pk_bf16_f32 v161, v88, v89
	s_waitcnt lgkmcnt(6)
	v_mfma_f32_32x32x16_bf16 v[98:113], v[174:177], v[154:157], 0
	v_lshl_add_u64 v[202:203], v[194:195], 0, s[4:5]
	s_add_i32 s100, s35, s33
	v_lshl_add_u64 v[204:205], v[202:203], 0, s[12:13]
	s_mov_b32 m0, s100
	s_nop 0
	global_load_lds_dwordx4 v[204:205], off
	v_add_f32_e32 v82, v92, v82
	v_add_f32_e32 v82, v93, v82
	v_add_f32_e32 v82, v94, v82
	v_add_f32_e32 v86, v95, v82
	v_cvt_pk_bf16_f32 v146, v90, v91
	v_cvt_pk_bf16_f32 v147, v92, v93
	s_waitcnt lgkmcnt(5)
	v_mfma_f32_32x32x16_bf16 v[114:129], v[190:193], v[150:153], v[114:129]
	ds_read_b64_tr_b16 v[82:83], v201 offset:24576
	ds_read_b64_tr_b16 v[84:85], v201 offset:25088
	v_add_f32_e32 v86, v96, v86
	v_add_f32_e32 v86, v97, v86
	v_add_f32_e32 v86, v66, v86
	v_add_f32_e32 v90, v67, v86
	v_cvt_pk_bf16_f32 v148, v94, v95
	v_cvt_pk_bf16_f32 v149, v96, v97
	s_waitcnt lgkmcnt(6)
	v_mfma_f32_32x32x16_bf16 v[98:113], v[178:181], v[150:153], v[98:113]
	ds_read_b64_tr_b16 v[86:87], v201 offset:28672
	ds_read_b64_tr_b16 v[88:89], v201 offset:29184
	v_add_f32_e32 v90, v68, v90
	v_add_f32_e32 v90, v69, v90
	v_add_f32_e32 v90, v70, v90
	v_add_f32_e32 v90, v71, v90
	v_cvt_pk_bf16_f32 v138, v66, v67
	v_cvt_pk_bf16_f32 v139, v68, v69
	s_waitcnt lgkmcnt(7)
	v_mfma_f32_32x32x16_bf16 v[114:129], v[182:185], v[142:145], v[114:129]
	ds_read_b64_tr_b16 v[66:67], v201 offset:32768
	ds_read_b64_tr_b16 v[68:69], v201 offset:33280
	v_add_f32_e32 v90, v72, v90
	v_add_f32_e32 v90, v73, v90
	v_add_f32_e32 v90, v74, v90
	v_add_f32_e32 v90, v75, v90
	v_cvt_pk_bf16_f32 v140, v70, v71
	v_cvt_pk_bf16_f32 v141, v72, v73
	s_waitcnt lgkmcnt(8)
	v_mfma_f32_32x32x16_bf16 v[98:113], v[166:169], v[142:145], v[98:113]
	v_lshl_add_u64 v[218:219], v[196:197], 0, s[4:5]
	s_lshl_b32 s100, s36, 1
	v_lshl_add_u64 v[222:223], v[218:219], 0, s[14:15]
	s_add_i32 s100, s100, s34
	s_mov_b32 m0, s100
	s_nop 0
	global_load_lds_dwordx4 v[222:223], off
	ds_read_b64_tr_b16 v[70:71], v201 offset:36864
	ds_read_b64_tr_b16 v[72:73], v201 offset:37376
	v_add_f32_e32 v90, v76, v90
	v_add_f32_e32 v90, v77, v90
	v_add_f32_e32 v90, v78, v90
	v_add_f32_e32 v90, v79, v90
	v_cvt_pk_bf16_f32 v130, v74, v75
	v_cvt_pk_bf16_f32 v131, v76, v77
	s_waitcnt lgkmcnt(9)
	v_mfma_f32_32x32x16_bf16 v[114:129], v[170:173], v[134:137], v[114:129]
	ds_read_b64_tr_b16 v[74:75], v201 offset:25600
	ds_read_b64_tr_b16 v[76:77], v201 offset:26112
	v_add_f32_e32 v90, v80, v90
	v_add_f32_e32 v90, v81, v90
	v_add_f32_e32 v200, 0, v90
	v_cvt_pk_bf16_f32 v132, v78, v79
	v_cvt_pk_bf16_f32 v133, v80, v81
	s_waitcnt lgkmcnt(10)
	v_mfma_f32_32x32x16_bf16 v[98:113], v[162:165], v[134:137], v[98:113]
	s_waitcnt lgkmcnt(8)
	v_mfma_f32_32x32x16_bf16 v[34:49], v[158:161], v[82:85], v[34:49]
	v_exp_f32_e32 v114, v114
	v_exp_f32_e32 v115, v115
	ds_read_b64_tr_b16 v[78:79], v201 offset:29696
	ds_read_b64_tr_b16 v[80:81], v201 offset:30208
	s_waitcnt lgkmcnt(8)
	v_mfma_f32_32x32x16_bf16 v[50:65], v[158:161], v[86:89], v[50:65]
	v_exp_f32_e32 v116, v116
	v_exp_f32_e32 v117, v117
	ds_read_b64_tr_b16 v[82:83], v201 offset:33792
	ds_read_b64_tr_b16 v[84:85], v201 offset:34304
	s_waitcnt lgkmcnt(8)
	v_mfma_f32_32x32x16_bf16 v[2:17], v[158:161], v[66:69], v[2:17]
	v_exp_f32_e32 v118, v118
	v_exp_f32_e32 v119, v119
	ds_read_b64_tr_b16 v[86:87], v201 offset:37888
	ds_read_b64_tr_b16 v[88:89], v201 offset:38400
	s_waitcnt lgkmcnt(8)
	v_mfma_f32_32x32x16_bf16 v[18:33], v[158:161], v[70:73], v[18:33]
	v_exp_f32_e32 v120, v120
	v_exp_f32_e32 v121, v121
	v_lshl_add_u64 v[220:221], v[198:199], 0, s[4:5]
	v_lshl_add_u64 v[224:225], v[220:221], 0, s[14:15]
	s_addk_i32 s100, 0x2000
	s_mov_b32 m0, s100
	s_nop 0
	global_load_lds_dwordx4 v[224:225], off
	ds_read_b64_tr_b16 v[70:71], v201 offset:26624
	ds_read_b64_tr_b16 v[72:73], v201 offset:27136
	v_add_u32_e32 v94, s8, v212
	ds_read_b128 v[90:93], v94
	ds_read_b128 v[66:69], v94 offset:512
	s_waitcnt lgkmcnt(10)
	v_mfma_f32_32x32x16_bf16 v[34:49], v[146:149], v[74:77], v[34:49]
	v_exp_f32_e32 v122, v122
	v_exp_f32_e32 v123, v123
	ds_read_b64_tr_b16 v[74:75], v201 offset:30720
	ds_read_b64_tr_b16 v[76:77], v201 offset:31232
	s_waitcnt lgkmcnt(10)
	v_mfma_f32_32x32x16_bf16 v[50:65], v[146:149], v[78:81], v[50:65]
	v_exp_f32_e32 v124, v124
	v_exp_f32_e32 v125, v125
	ds_read_b64_tr_b16 v[78:79], v201 offset:34816
	ds_read_b64_tr_b16 v[80:81], v201 offset:35328
	s_waitcnt lgkmcnt(10)
	v_mfma_f32_32x32x16_bf16 v[2:17], v[146:149], v[82:85], v[2:17]
	v_exp_f32_e32 v126, v126
	v_exp_f32_e32 v127, v127
	ds_read_b64_tr_b16 v[82:83], v201 offset:38912
	ds_read_b64_tr_b16 v[84:85], v201 offset:39424
	ds_read_b128 v[168:171], v94 offset:2048
	ds_read_b128 v[172:175], v94 offset:2560
	s_waitcnt lgkmcnt(12)
	v_mfma_f32_32x32x16_bf16 v[18:33], v[146:149], v[86:89], v[18:33]
	v_exp_f32_e32 v128, v128
	v_exp_f32_e32 v129, v129
	ds_read_b64_tr_b16 v[86:87], v201 offset:27648
	ds_read_b64_tr_b16 v[88:89], v201 offset:28160
	s_waitcnt lgkmcnt(12)
	v_mfma_f32_32x32x16_bf16 v[34:49], v[138:141], v[70:73], v[34:49]
	v_exp_f32_e32 v98, v98
	v_exp_f32_e32 v99, v99
	ds_read_b64_tr_b16 v[70:71], v201 offset:31744
	ds_read_b64_tr_b16 v[72:73], v201 offset:32256
	s_waitcnt lgkmcnt(10)
; #define WAIT_BAR(N) asm volatile("s_waitcnt vmcnt(" #N ") lgkmcnt(0)\n\ts_barrier":::"memory")
;   #define RESC() do{ if(resc){ asm volatile("s_waitcnt lgkmcnt(0)":::"memory"); \
;       _Pragma("unroll") for(int d_=0;d_<2;++d_) _Pragma("unroll") for(int r=0;r<16;++r)o[d_][r]*=wsf[crow(r,hi)]; } }while(0)
;   #define ROT() do{sl_prev=sl_cur;sl_cur=sl_next;sl_next=(sl_next==(NSLOT-1)*SLOTB)?0:sl_next+SLOTB;}while(0)
;   #define RESC() do{ if(resc){ asm volatile("s_waitcnt lgkmcnt(0)":::"memory"); \
;       _Pragma("unroll") for(int d_=0;d_<4;++d_) _Pragma("unroll") for(int r=0;r<16;++r)o[d_][r]*=wsf[crow(r,hi)]; } }while(0)
;   #define ROT() do{sl_prev=sl_cur;sl_cur=sl_next;sl_next=(sl_next==(NSLOT-1)*SLOTB)?0:sl_next+SLOTB;}while(0)
; template<int THRL,bool NOMAX=false> __device__ __forceinline__ void attn_unit_v128(const bf16*Qu,int qp,const bf16*__restrict__ Kh,int kp,const bf16*__restrict__ Vh,int vp,bf16*Ou,int op,int NT,char*shm,int tid_in){
;     ...
;   int t=1;
;   for(;t+5<NT;t+=2){
;     STEP(pB0,pB1,pA0,pA1,t,true,true,true);     WAIT_BAR(3); RESC(); ROT();
;     STEP(pA0,pA1,pB0,pB1,t+1,true,true,true);   WAIT_BAR(3); RESC(); ROT();
	v_mfma_f32_32x32x16_bf16 v[50:65], v[138:141], v[74:77], v[50:65]
	v_exp_f32_e32 v100, v100
	v_exp_f32_e32 v101, v101
	ds_read_b64_tr_b16 v[74:75], v201 offset:35840
	ds_read_b64_tr_b16 v[76:77], v201 offset:36352
	ds_read_b128 v[176:179], v94 offset:4096
	ds_read_b128 v[180:183], v94 offset:4608
	s_waitcnt lgkmcnt(12)
	v_mfma_f32_32x32x16_bf16 v[2:17], v[138:141], v[78:81], v[2:17]
	v_exp_f32_e32 v102, v102
	v_exp_f32_e32 v103, v103
	ds_read_b64_tr_b16 v[78:79], v201 offset:39936
	ds_read_b64_tr_b16 v[80:81], v201 offset:40448
	s_waitcnt lgkmcnt(12)
	v_mfma_f32_32x32x16_bf16 v[18:33], v[138:141], v[82:85], v[18:33]
	v_exp_f32_e32 v104, v104
	v_exp_f32_e32 v105, v105
	s_waitcnt lgkmcnt(8)
	v_mfma_f32_32x32x16_bf16 v[34:49], v[130:133], v[86:89], v[34:49]
	v_exp_f32_e32 v106, v106
	v_exp_f32_e32 v107, v107
	ds_read_b128 v[184:187], v94 offset:6144
	ds_read_b128 v[188:191], v94 offset:6656
	s_waitcnt lgkmcnt(8)
	v_mfma_f32_32x32x16_bf16 v[50:65], v[130:133], v[70:73], v[50:65]
	v_exp_f32_e32 v108, v108
	v_exp_f32_e32 v109, v109
	s_waitcnt lgkmcnt(6)
	v_mfma_f32_32x32x16_bf16 v[2:17], v[130:133], v[74:77], v[2:17]
	v_exp_f32_e32 v110, v110
	v_exp_f32_e32 v111, v111
	s_waitcnt lgkmcnt(2)
	v_mfma_f32_32x32x16_bf16 v[18:33], v[130:133], v[78:81], v[18:33]
	v_exp_f32_e32 v112, v112
	v_exp_f32_e32 v113, v113
	s_waitcnt vmcnt(3) lgkmcnt(0)
	s_barrier
	s_add_i32 s9, s36, 0x2000
	s_cmpk_lg_i32 s36, 0x4000
	s_cselect_b32 s35, s9, 0
	v_mfma_f32_32x32x16_bf16 v[82:97], v[90:93], v[154:157], 0
	v_add_f32_e32 v70, v114, v115
	v_add_f32_e32 v70, v116, v70
	v_add_f32_e32 v70, v117, v70
	v_add_f32_e32 v70, v118, v70
	v_add_f32_e32 v70, v119, v70
	v_cvt_pk_bf16_f32 v158, v114, v115
	v_cvt_pk_bf16_f32 v159, v116, v117
	v_lshl_add_u32 v201, s7, 1, v214
	s_nop 0
	v_add_f32_e32 v70, v120, v70
	v_add_f32_e32 v70, v121, v70
	v_add_f32_e32 v70, v122, v70
	v_add_f32_e32 v114, v123, v70
	v_mfma_f32_32x32x16_bf16 v[66:81], v[66:69], v[154:157], 0
	v_cvt_pk_bf16_f32 v160, v118, v119
	v_cvt_pk_bf16_f32 v161, v120, v121
	s_add_i32 s101, s36, s33
	v_lshl_add_u64 v[228:229], v[202:203], 0, s[18:19]
	s_mov_b32 m0, s101
	s_nop 0
	global_load_lds_dwordx4 v[228:229], off
	v_mfma_f32_32x32x16_bf16 v[82:97], v[168:171], v[150:153], v[82:97]
	v_add_f32_e32 v114, v124, v114
	v_add_f32_e32 v114, v125, v114
	v_add_f32_e32 v114, v126, v114
	v_add_f32_e32 v118, v127, v114
	v_cvt_pk_bf16_f32 v146, v122, v123
	v_cvt_pk_bf16_f32 v147, v124, v125
	ds_read_b64_tr_b16 v[114:115], v201 offset:24576
	ds_read_b64_tr_b16 v[116:117], v201 offset:25088
	v_mfma_f32_32x32x16_bf16 v[66:81], v[172:175], v[150:153], v[66:81]
	v_add_f32_e32 v118, v128, v118
	v_add_f32_e32 v118, v129, v118
	v_add_f32_e32 v118, v98, v118
	v_add_f32_e32 v122, v99, v118
	v_cvt_pk_bf16_f32 v148, v126, v127
	v_cvt_pk_bf16_f32 v149, v128, v129
	ds_read_b64_tr_b16 v[118:119], v201 offset:28672
	ds_read_b64_tr_b16 v[120:121], v201 offset:29184
	v_mfma_f32_32x32x16_bf16 v[82:97], v[176:179], v[142:145], v[82:97]
	v_add_f32_e32 v122, v100, v122
	v_add_f32_e32 v122, v101, v122
	v_add_f32_e32 v122, v102, v122
	v_add_f32_e32 v122, v103, v122
	v_cvt_pk_bf16_f32 v138, v98, v99
	v_cvt_pk_bf16_f32 v139, v100, v101
	ds_read_b64_tr_b16 v[98:99], v201 offset:32768
	ds_read_b64_tr_b16 v[100:101], v201 offset:33280
	v_mfma_f32_32x32x16_bf16 v[66:81], v[180:183], v[142:145], v[66:81]
	v_add_f32_e32 v122, v104, v122
	v_add_f32_e32 v122, v105, v122
	v_add_f32_e32 v122, v106, v122
	v_add_f32_e32 v122, v107, v122
	v_cvt_pk_bf16_f32 v140, v102, v103
	v_cvt_pk_bf16_f32 v141, v104, v105
	s_lshl_b32 s101, s35, 1
	v_lshl_add_u64 v[230:231], v[218:219], 0, s[16:17]
	s_add_i32 s101, s101, s34
	s_mov_b32 m0, s101
	s_nop 0
	global_load_lds_dwordx4 v[230:231], off
	ds_read_b64_tr_b16 v[102:103], v201 offset:36864
	ds_read_b64_tr_b16 v[104:105], v201 offset:37376
	s_waitcnt lgkmcnt(9)
	v_mfma_f32_32x32x16_bf16 v[82:97], v[184:187], v[134:137], v[82:97]
	v_add_f32_e32 v122, v108, v122
	v_add_f32_e32 v122, v109, v122
	v_add_f32_e32 v122, v110, v122
	v_add_f32_e32 v122, v111, v122
	v_cvt_pk_bf16_f32 v130, v106, v107
	v_cvt_pk_bf16_f32 v131, v108, v109
	ds_read_b64_tr_b16 v[106:107], v201 offset:25600
	ds_read_b64_tr_b16 v[108:109], v201 offset:26112
	s_waitcnt lgkmcnt(10)
	v_mfma_f32_32x32x16_bf16 v[66:81], v[188:191], v[134:137], v[66:81]
	v_add_f32_e32 v122, v112, v122
	v_add_f32_e32 v122, v113, v122
	v_add_f32_e32 v122, 0, v122
	v_cvt_pk_bf16_f32 v132, v110, v111
	v_cvt_pk_bf16_f32 v133, v112, v113
	s_waitcnt lgkmcnt(8)
; #define WAIT_BAR(N) asm volatile("s_waitcnt vmcnt(" #N ") lgkmcnt(0)\n\ts_barrier":::"memory")
;   #define RESC() do{ if(resc){ asm volatile("s_waitcnt lgkmcnt(0)":::"memory"); \
;       _Pragma("unroll") for(int d_=0;d_<2;++d_) _Pragma("unroll") for(int r=0;r<16;++r)o[d_][r]*=wsf[crow(r,hi)]; } }while(0)
;   #define ROT() do{sl_prev=sl_cur;sl_cur=sl_next;sl_next=(sl_next==(NSLOT-1)*SLOTB)?0:sl_next+SLOTB;}while(0)
;   #define RESC() do{ if(resc){ asm volatile("s_waitcnt lgkmcnt(0)":::"memory"); \
;       _Pragma("unroll") for(int d_=0;d_<4;++d_) _Pragma("unroll") for(int r=0;r<16;++r)o[d_][r]*=wsf[crow(r,hi)]; } }while(0)
;   #define ROT() do{sl_prev=sl_cur;sl_cur=sl_next;sl_next=(sl_next==(NSLOT-1)*SLOTB)?0:sl_next+SLOTB;}while(0)
; template<int THRL,bool NOMAX=false> __device__ __forceinline__ void attn_unit_v128(const bf16*Qu,int qp,const bf16*__restrict__ Kh,int kp,const bf16*__restrict__ Vh,int vp,bf16*Ou,int op,int NT,char*shm,int tid_in){
;     ...
;   int t=1;
;   for(;t+5<NT;t+=2){
;     STEP(pB0,pB1,pA0,pA1,t,true,true,true);     WAIT_BAR(3); RESC(); ROT();
;     STEP(pA0,pA1,pB0,pB1,t+1,true,true,true);   WAIT_BAR(3); RESC(); ROT();
;   }
	v_mfma_f32_32x32x16_bf16 v[34:49], v[158:161], v[114:117], v[34:49]
	v_exp_f32_e32 v82, v82
	v_exp_f32_e32 v83, v83
	ds_read_b64_tr_b16 v[110:111], v201 offset:29696
	ds_read_b64_tr_b16 v[112:113], v201 offset:30208
	s_waitcnt lgkmcnt(8)
	v_mfma_f32_32x32x16_bf16 v[50:65], v[158:161], v[118:121], v[50:65]
	v_exp_f32_e32 v84, v84
	v_exp_f32_e32 v85, v85
	ds_read_b64_tr_b16 v[114:115], v201 offset:33792
	ds_read_b64_tr_b16 v[116:117], v201 offset:34304
	s_waitcnt lgkmcnt(8)
	v_mfma_f32_32x32x16_bf16 v[2:17], v[158:161], v[98:101], v[2:17]
	v_exp_f32_e32 v86, v86
	v_exp_f32_e32 v87, v87
	ds_read_b64_tr_b16 v[98:99], v201 offset:37888
	ds_read_b64_tr_b16 v[100:101], v201 offset:38400
	s_waitcnt lgkmcnt(8)
	v_mfma_f32_32x32x16_bf16 v[18:33], v[158:161], v[102:105], v[18:33]
	v_exp_f32_e32 v88, v88
	v_exp_f32_e32 v89, v89
	v_lshl_add_u64 v[232:233], v[220:221], 0, s[16:17]
	s_addk_i32 s101, 0x2000
	s_mov_b32 m0, s101
	s_nop 0
	global_load_lds_dwordx4 v[232:233], off
	ds_read_b64_tr_b16 v[102:103], v201 offset:26624
	ds_read_b64_tr_b16 v[104:105], v201 offset:27136
	v_add_u32_e32 v118, s35, v212
	ds_read_b128 v[186:189], v118
	ds_read_b128 v[174:177], v118 offset:512
	s_waitcnt lgkmcnt(10)
	v_mfma_f32_32x32x16_bf16 v[34:49], v[146:149], v[106:109], v[34:49]
	v_exp_f32_e32 v90, v90
	v_exp_f32_e32 v91, v91
	ds_read_b64_tr_b16 v[106:107], v201 offset:30720
	ds_read_b64_tr_b16 v[108:109], v201 offset:31232
	s_waitcnt lgkmcnt(10)
	v_mfma_f32_32x32x16_bf16 v[50:65], v[146:149], v[110:113], v[50:65]
	v_exp_f32_e32 v92, v92
	v_exp_f32_e32 v93, v93
	ds_read_b64_tr_b16 v[110:111], v201 offset:34816
	ds_read_b64_tr_b16 v[112:113], v201 offset:35328
	s_waitcnt lgkmcnt(10)
	v_mfma_f32_32x32x16_bf16 v[2:17], v[146:149], v[114:117], v[2:17]
	v_exp_f32_e32 v94, v94
	v_exp_f32_e32 v95, v95
	ds_read_b64_tr_b16 v[114:115], v201 offset:38912
	ds_read_b64_tr_b16 v[116:117], v201 offset:39424
	ds_read_b128 v[190:193], v118 offset:2048
	ds_read_b128 v[178:181], v118 offset:2560
	s_waitcnt lgkmcnt(12)
	v_mfma_f32_32x32x16_bf16 v[18:33], v[146:149], v[98:101], v[18:33]
	v_exp_f32_e32 v96, v96
	v_exp_f32_e32 v97, v97
	ds_read_b64_tr_b16 v[98:99], v201 offset:27648
	ds_read_b64_tr_b16 v[100:101], v201 offset:28160
	s_waitcnt lgkmcnt(12)
	v_mfma_f32_32x32x16_bf16 v[34:49], v[138:141], v[102:105], v[34:49]
	v_exp_f32_e32 v66, v66
	v_exp_f32_e32 v67, v67
	ds_read_b64_tr_b16 v[102:103], v201 offset:31744
	ds_read_b64_tr_b16 v[104:105], v201 offset:32256
	s_waitcnt lgkmcnt(10)
	v_mfma_f32_32x32x16_bf16 v[50:65], v[138:141], v[106:109], v[50:65]
	v_exp_f32_e32 v68, v68
	v_exp_f32_e32 v69, v69
	ds_read_b64_tr_b16 v[106:107], v201 offset:35840
	ds_read_b64_tr_b16 v[108:109], v201 offset:36352
	ds_read_b128 v[182:185], v118 offset:4096
	ds_read_b128 v[166:169], v118 offset:4608
	s_waitcnt lgkmcnt(12)
	v_mfma_f32_32x32x16_bf16 v[2:17], v[138:141], v[110:113], v[2:17]
	v_exp_f32_e32 v70, v70
	v_exp_f32_e32 v71, v71
	ds_read_b64_tr_b16 v[110:111], v201 offset:39936
	ds_read_b64_tr_b16 v[112:113], v201 offset:40448
	s_waitcnt lgkmcnt(12)
	v_mfma_f32_32x32x16_bf16 v[18:33], v[138:141], v[114:117], v[18:33]
	v_exp_f32_e32 v72, v72
	v_exp_f32_e32 v73, v73
	s_waitcnt lgkmcnt(8)
	v_mfma_f32_32x32x16_bf16 v[34:49], v[130:133], v[98:101], v[34:49]
	v_exp_f32_e32 v74, v74
	v_exp_f32_e32 v75, v75
	ds_read_b128 v[170:173], v118 offset:6144
	ds_read_b128 v[162:165], v118 offset:6656
	s_waitcnt lgkmcnt(8)
	v_mfma_f32_32x32x16_bf16 v[50:65], v[130:133], v[102:105], v[50:65]
	v_exp_f32_e32 v76, v76
	v_exp_f32_e32 v77, v77
	s_waitcnt lgkmcnt(6)
	v_mfma_f32_32x32x16_bf16 v[2:17], v[130:133], v[106:109], v[2:17]
	v_exp_f32_e32 v78, v78
	v_exp_f32_e32 v79, v79
	s_waitcnt lgkmcnt(2)
	v_mfma_f32_32x32x16_bf16 v[18:33], v[130:133], v[110:113], v[18:33]
	v_exp_f32_e32 v80, v80
	v_exp_f32_e32 v81, v81
	s_add_i32 s7, s35, 0x2000
	s_cmpk_lg_i32 s35, 0x4000
	s_mov_b32 s9, s36
	s_cselect_b32 s36, s7, 0
	s_add_i32 s10, s6, 2
	s_waitcnt vmcnt(3) lgkmcnt(0)
	s_barrier
	s_add_u32 s4, s4, 0x20000
	v_add_f32_e32 v98, v210, v200
	s_addc_u32 s5, s5, 0
	s_cmp_ge_u32 s10, s75
	v_add_f32_e32 v210, v98, v122
	s_cbranch_scc0 .LBB0_798
	s_add_i32 s86, s6, -3
	s_add_i32 s4, s86, 1
	s_cmp_ge_u32 s4, s75
	s_mov_b64 s[4:5], -1
	s_cbranch_scc0 .LBB0_802
	s_branch .LBB0_801

; __global__ void __launch_bounds__(NWAVES * 64, 2) fwd_kernel(Args args) {
	.amdhsa_kernel _Z10fwd_kernel4Args
		.amdhsa_group_segment_fixed_size 0
		.amdhsa_private_segment_fixed_size 0
		.amdhsa_kernarg_size 512
		.amdhsa_user_sgpr_count 2
		.amdhsa_user_sgpr_dispatch_ptr 0
		.amdhsa_user_sgpr_queue_ptr 0
		.amdhsa_user_sgpr_kernarg_segment_ptr 1
		.amdhsa_user_sgpr_dispatch_id 0
		.amdhsa_user_sgpr_kernarg_preload_length 0
		.amdhsa_user_sgpr_kernarg_preload_offset 0
		.amdhsa_user_sgpr_private_segment_size 0
		.amdhsa_uses_dynamic_stack 0
		.amdhsa_enable_private_segment 0
		.amdhsa_system_sgpr_workgroup_id_x 1
		.amdhsa_system_sgpr_workgroup_id_y 0
		.amdhsa_system_sgpr_workgroup_id_z 0
		.amdhsa_system_sgpr_workgroup_info 0
		.amdhsa_system_vgpr_workitem_id 0
		.amdhsa_next_free_vgpr 256
		.amdhsa_next_free_sgpr 102
		.amdhsa_accum_offset 256
		.amdhsa_reserve_vcc 1
		.amdhsa_float_round_mode_32 0
		.amdhsa_float_round_mode_16_64 0
		.amdhsa_float_denorm_mode_32 3
		.amdhsa_float_denorm_mode_16_64 3
		.amdhsa_dx10_clamp 1
		.amdhsa_ieee_mode 1
		.amdhsa_fp16_overflow 0
		.amdhsa_tg_split 0
		.amdhsa_exception_fp_ieee_invalid_op 0
		.amdhsa_exception_fp_denorm_src 0
		.amdhsa_exception_fp_ieee_div_zero 0
		.amdhsa_exception_fp_ieee_overflow 0
		.amdhsa_exception_fp_ieee_underflow 0
		.amdhsa_exception_fp_ieee_inexact 0
		.amdhsa_exception_int_div_zero 0
	.end_amdhsa_kernel

; __global__ void __launch_bounds__(NWAVES * 64, 2) fwd_kernel(Args args) {
amdhsa.kernels:
  - .agpr_count:     0
    .args:
      - .offset:         0
        .size:           256
        .value_kind:     by_value
      - .offset:         256
        .size:           4
        .value_kind:     hidden_block_count_x
      - .offset:         260
        .size:           4
        .value_kind:     hidden_block_count_y
      - .offset:         264
        .size:           4
        .value_kind:     hidden_block_count_z
      - .offset:         268
        .size:           2
        .value_kind:     hidden_group_size_x
      - .offset:         270
        .size:           2
        .value_kind:     hidden_group_size_y
      - .offset:         272
        .size:           2
        .value_kind:     hidden_group_size_z
      - .offset:         274
        .size:           2
        .value_kind:     hidden_remainder_x
      - .offset:         276
        .size:           2
        .value_kind:     hidden_remainder_y
      - .offset:         278
        .size:           2
        .value_kind:     hidden_remainder_z
      - .offset:         296
        .size:           8
        .value_kind:     hidden_global_offset_x
      - .offset:         304
        .size:           8
        .value_kind:     hidden_global_offset_y
      - .offset:         312
        .size:           8
        .value_kind:     hidden_global_offset_z
      - .offset:         320
        .size:           2
        .value_kind:     hidden_grid_dims
      - .offset:         376
        .size:           4
        .value_kind:     hidden_dynamic_lds_size
    .group_segment_fixed_size: 0
    .kernarg_segment_align: 8
    .kernarg_segment_size: 512
    .language:       OpenCL C
    .language_version:
      - 2
      - 0
    .max_flat_workgroup_size: 512
    .name:           _Z10fwd_kernel4Args
    .private_segment_fixed_size: 0
    .sgpr_count:     108
    .sgpr_spill_count: 167
    .symbol:         _Z10fwd_kernel4Args.kd
    .uniform_work_group_size: 1
    .uses_dynamic_stack: false
    .vgpr_count:     256
    .vgpr_spill_count: 0
    .wavefront_size: 64
